# R7_CA: register back-substitution, S3 and the T-inverse stages with batched LDS reads, zero-operand MFMAs dropped
# speedup vs baseline: 1.0756x; 1.0341x over previous
; __device__ __forceinline__ bfr f2b(float f) { return (bfr)(cvtpk(f, f) & 0xffffu); }
; __device__ __forceinline__ unsigned pk2(float a, float b) { return cvtpk(a, b); }
; __device__ __forceinline__ void ph_r7_ca(const P& p, int j, int win, char* smem) {
;     ...
;       for (int e = 0; e < 8; e++) { kr[e] = k8[e] * kkp[col + e]; ss += kr[e] * kr[e]; }
;       ss += __shfl_xor(ss, 1); ss += __shfl_xor(ss, 2); ss += __shfl_xor(ss, 4);
;       const float inv = __builtin_amdgcn_rsqf(fmaxf(ss, 1e-24f));
;       float bon = 0.f, o0[8], o1[8], o2[8], o3[8], o4[8], o5[8];
; #pragma unroll
;       for (int e = 0; e < 8; e++) {
;         const float cw = LW[tau * 64 + sc * 8 + e], cwm = tau > 0 ? LW[(tau - 1) * 64 + sc * 8 + e] : 0.f, cwl = LW[63 * 64 + sc * 8 + e], a = AT[tau * 64 + sc * 8 + e];
;         const float ka = kr[e] * inv, be = a * ka, kd = k8[e] * (1.f + (a - 1.f) * kap[col + e]); bon += r8[e] * kd * rkp[col + e];
;         const float e2 = __expf(-cw), e4 = __expf(cwl - cw);
;         o0[e] = ka * __expf(cwm); o1[e] = be * e2; o2[e] = kd * e2; o3[e] = r8[e] * __expf(cw); o4[e] = be * e4; o5[e] = kd * e4;
;         if (tau == 63) WL[sc * 8 + e] = __expf(cwl);
;       }
;       bon += __shfl_xor(bon, 1); bon += __shfl_xor(bon, 2); bon += __shfl_xor(bon, 4);
;       if (sc == 0) BON[((size_t)d * R_ + row) * 16 + h] = bon;
;       *(uint4*)(CSLOT(0) + tau * CS + sc * 8) = uint4{pk2(o0[0], o0[1]), pk2(o0[2], o0[3]), pk2(o0[4], o0[5]), pk2(o0[6], o0[7])};
;       *(uint4*)(CSLOT(1) + tau * CS + sc * 8) = uint4{pk2(o1[0], o1[1]), pk2(o1[2], o1[3]), pk2(o1[4], o1[5]), pk2(o1[6], o1[7])};
;       *(uint4*)(CSLOT(2) + tau * CS + sc * 8) = uint4{pk2(o2[0], o2[1]), pk2(o2[2], o2[3]), pk2(o2[4], o2[5]), pk2(o2[6], o2[7])};
;       *(uint4*)(CSLOT(3) + tau * CS + sc * 8) = uint4{pk2(o3[0], o3[1]), pk2(o3[2], o3[3]), pk2(o3[4], o3[5]), pk2(o3[6], o3[7])};
; #pragma unroll
;       for (int e = 0; e < 8; e++) { CSLOT(4)[(sc * 8 + e) * CS + tau] = f2b(o0[e]); CSLOT(5)[(sc * 8 + e) * CS + tau] = f2b(o4[e]); CSLOT(6)[(sc * 8 + e) * CS + tau] = f2b(o5[e]); }
.LBB0_224:
	s_or_b64 exec, exec, s[30:31]
	v_mul_f32_e32 v228, 0x3fb8aa3b, v230
	v_exp_f32_e32 v228, v228
	v_add_f32_e32 v2, v219, v220
	v_max_f32_e32 v2, 0x179abe15, v2
	v_rsq_f32_e32 v6, v2
	v_mul_f32_e32 v228, v228, v5
	v_sub_f32_e32 v5, v227, v224
	v_mul_f32_e32 v178, 0xbfb8aa3b, v224
	v_mul_f32_e32 v5, 0x3fb8aa3b, v5
	v_exp_f32_e32 v178, v178
	v_exp_f32_e32 v179, v236
	v_exp_f32_e32 v5, v5
	v_exp_f32_e32 v218, v218
	v_mul_f32_e32 v2, v215, v6
	v_mul_f32_e32 v7, v2, v241
	v_mul_f32_e32 v2, v2, v179
	v_mul_f32_e32 v179, v178, v7
	v_mul_f32_e32 v178, v178, v45
	v_mul_f32_e32 v215, 0x3fb8aa3b, v224
	v_mul_f32_e32 v224, v5, v7
	v_mul_f32_e32 v45, v5, v45
	v_mul_f32_e32 v5, v28, v6
	v_mul_f32_e32 v7, v5, v223
	v_mul_f32_e32 v218, v5, v218
	v_mul_f32_e32 v5, 0x3fb8aa3b, v212
	v_exp_f32_e32 v5, v5
	v_exp_f32_e32 v217, v217
	v_sub_f32_e32 v221, v221, v216
	v_mul_f32_e32 v28, 0xbfb8aa3b, v212
	v_mul_f32_e32 v213, v5, v213
	v_mul_f32_e32 v5, v25, v6
	v_mul_f32_e32 v25, v5, v222
	v_mul_f32_e32 v217, v5, v217
	v_mul_f32_e32 v5, 0x3fb8aa3b, v216
	v_exp_f32_e32 v5, v5
	v_mul_f32_e32 v222, 0xbfb8aa3b, v216
	v_exp_f32_e32 v28, v28
	v_exp_f32_e32 v27, v27
	v_mul_f32_e32 v216, v5, v4
	v_sub_f32_e32 v4, v214, v212
	v_mul_f32_e32 v4, 0x3fb8aa3b, v4
	v_exp_f32_e32 v4, v4
	v_mul_f32_e32 v223, v28, v7
	v_mul_f32_e32 v28, v28, v47
	v_sub_f32_e32 v30, v30, v26
	v_mul_f32_e32 v212, v4, v7
	v_mul_f32_e32 v47, v4, v47
	v_mul_f32_e32 v4, v22, v6
	v_exp_f32_e32 v22, v29
	v_mul_f32_e32 v5, v4, v41
	v_mul_f32_e32 v7, 0xbfb8aa3b, v23
	v_exp_f32_e32 v7, v7
	v_mul_f32_e32 v22, v4, v22
	v_mul_f32_e32 v4, 0x3fb8aa3b, v23
	v_exp_f32_e32 v4, v4
	v_mul_f32_e32 v29, v7, v5
	v_mul_f32_e32 v41, v7, v49
	v_mul_f32_e32 v30, 0x3fb8aa3b, v30
	v_mul_f32_e32 v51, v4, v51
	v_mul_f32_e32 v4, v19, v6
	v_mul_f32_e32 v7, v4, v31
	v_mul_f32_e32 v27, v4, v27
	v_mul_f32_e32 v4, 0x3fb8aa3b, v26
	v_exp_f32_e32 v4, v4
	v_mul_f32_e32 v19, 0xbfb8aa3b, v26
	v_exp_f32_e32 v19, v19
	v_exp_f32_e32 v30, v30
	v_mul_f32_e32 v3, v4, v3
	v_sub_f32_e32 v4, v24, v23
	v_mul_f32_e32 v4, 0x3fb8aa3b, v4
	v_exp_f32_e32 v4, v4
	v_mul_f32_e32 v50, v50, v6
	v_exp_f32_e32 v215, v215
	v_mul_f32_e32 v31, v19, v7
	v_mul_f32_e32 v23, v4, v5
	v_mul_f32_e32 v24, v4, v49
	v_mul_f32_e32 v4, v14, v6
	v_exp_f32_e32 v14, v18
	v_mul_f32_e32 v5, v4, v21
	v_mul_f32_e32 v26, v30, v7
	v_mul_f32_e32 v7, 0xbfb8aa3b, v13
	v_mul_f32_e32 v14, v4, v14
	v_mul_f32_e32 v4, 0x3fb8aa3b, v13
	v_exp_f32_e32 v4, v4
	v_exp_f32_e32 v7, v7
	v_mul_f32_e32 v215, v215, v225
	v_sub_f32_e32 v225, v237, v230
	v_mul_f32_e32 v11, v4, v11
	v_mul_f32_e32 v4, v12, v6
	v_exp_f32_e32 v12, v17
	v_mul_f32_e32 v6, v4, v20
	v_sub_f32_e32 v0, v0, v16
	v_mul_f32_e32 v220, 0xbfb8aa3b, v230
	v_mul_f32_e32 v12, v4, v12
	v_mul_f32_e32 v4, 0x3fb8aa3b, v16
	v_exp_f32_e32 v4, v4
	v_mul_f32_e32 v225, 0x3fb8aa3b, v225
	s_waitcnt lgkmcnt(0)
	v_exp_f32_e32 v226, v232
	v_mul_f32_e32 v18, v7, v5
	v_mul_f32_e32 v9, v4, v9
	v_sub_f32_e32 v4, v15, v13
	v_mul_f32_e32 v21, v7, v8
	v_mul_f32_e32 v7, 0xbfb8aa3b, v16
	v_mul_f32_e32 v0, 0x3fb8aa3b, v0
	v_mul_f32_e32 v4, 0x3fb8aa3b, v4
	v_exp_f32_e32 v220, v220
	v_exp_f32_e32 v225, v225
	v_exp_f32_e32 v222, v222
	v_exp_f32_e32 v7, v7
	v_exp_f32_e32 v0, v0
	v_exp_f32_e32 v4, v4
	v_mul_f32_e32 v219, v50, v238
	v_mul_f32_e32 v50, v50, v226
	v_mul_f32_e32 v226, v220, v219
	v_mul_f32_e32 v220, v220, v43
	v_mul_f32_e32 v219, v225, v219
	v_mul_f32_e32 v43, v225, v43
	v_mul_f32_e32 v225, v222, v25
	v_mul_f32_e32 v17, v7, v6
	v_mul_f32_e32 v20, v7, v10
	v_mul_f32_e32 v16, v0, v6
	v_mul_f32_e32 v0, v0, v10
	v_mul_f32_e32 v10, v4, v5
	v_mul_f32_e32 v8, v4, v8
	v_cvt_pk_bf16_f32 v4, v14, v12
	v_cvt_pk_bf16_f32 v5, v22, v27
	v_cvt_pk_bf16_f32 v6, v218, v217
	v_cvt_pk_bf16_f32 v7, v2, v50
	v_mul_f32_e32 v222, v222, v46
	v_mul_f32_e32 v19, v19, v48
	ds_write_b128 v61, v[4:7]
	v_cvt_pk_bf16_f32 v4, v18, v17
	v_cvt_pk_bf16_f32 v5, v29, v31
	v_cvt_pk_bf16_f32 v6, v223, v225
	v_cvt_pk_bf16_f32 v7, v179, v226
	ds_write_b128 v61, v[4:7] offset:9216
	v_cvt_pk_bf16_f32 v4, v21, v20
	v_cvt_pk_bf16_f32 v5, v41, v19
	v_cvt_pk_bf16_f32 v6, v28, v222
	v_cvt_pk_bf16_f32 v7, v178, v220
	ds_write_b128 v61, v[4:7] offset:18432
	v_cvt_pk_bf16_f32 v4, v11, v9
	v_cvt_pk_bf16_f32 v5, v51, v3
	v_cvt_pk_bf16_f32 v6, v213, v216
	v_cvt_pk_bf16_f32 v7, v215, v228
	v_cvt_pk_bf16_f32 v0, v0, s0
	ds_write_b128 v61, v[4:7] offset:27648
	ds_write_b16 v108, v0 offset:55440
	v_cvt_pk_bf16_f32 v0, v22, s0
	ds_write_b16 v108, v0 offset:37152
	v_cvt_pk_bf16_f32 v0, v23, s0
	ds_write_b16 v108, v0 offset:46368
	v_cvt_pk_bf16_f32 v0, v24, s0
	ds_write_b16 v108, v0 offset:55584
	v_cvt_pk_bf16_f32 v0, v27, s0
	v_mul_f32_e32 v221, 0x3fb8aa3b, v221
	v_mul_f32_e32 v30, v30, v48
	ds_write_b16 v108, v0 offset:37296
	v_cvt_pk_bf16_f32 v0, v26, s0
	v_exp_f32_e32 v221, v221
	ds_write_b16 v108, v0 offset:46512
	v_cvt_pk_bf16_f32 v0, v30, s0
	ds_write_b16 v108, v0 offset:55728
	v_cvt_pk_bf16_f32 v0, v218, s0
	ds_write_b16 v108, v0 offset:37440
	v_cvt_pk_bf16_f32 v0, v212, s0
	ds_write_b16 v108, v0 offset:46656
	v_cvt_pk_bf16_f32 v0, v47, s0
	v_mul_f32_e32 v25, v221, v25
	ds_write_b16 v108, v0 offset:55872
	v_cvt_pk_bf16_f32 v0, v217, s0
	v_mul_f32_e32 v46, v221, v46
	ds_write_b16 v108, v0 offset:37584
	v_cvt_pk_bf16_f32 v0, v25, s0
	ds_write_b16 v108, v0 offset:46800
	v_cvt_pk_bf16_f32 v0, v46, s0
	ds_write_b16 v108, v0 offset:56016
	v_cvt_pk_bf16_f32 v0, v2, s0
	v_cvt_pk_bf16_f32 v3, v14, s0
	ds_write_b16 v108, v0 offset:37728
	v_cvt_pk_bf16_f32 v0, v224, s0
	ds_write_b16 v108, v3 offset:36864
	v_cvt_pk_bf16_f32 v3, v10, s0
	ds_write_b16 v108, v0 offset:46944
	v_cvt_pk_bf16_f32 v0, v45, s0
	ds_write_b16 v108, v3 offset:46080
	v_cvt_pk_bf16_f32 v3, v8, s0
	ds_write_b16 v108, v0 offset:56160
	v_cvt_pk_bf16_f32 v0, v50, s0
	ds_write_b16 v108, v3 offset:55296
	v_cvt_pk_bf16_f32 v3, v12, s0
	ds_write_b16 v108, v0 offset:37872
	v_cvt_pk_bf16_f32 v0, v219, s0
	ds_write_b16 v108, v3 offset:37008
	v_cvt_pk_bf16_f32 v3, v16, s0
	ds_write_b16 v108, v0 offset:47088
	v_cvt_pk_bf16_f32 v0, v43, s0
	ds_write_b16 v108, v3 offset:46224
	ds_write_b16 v108, v0 offset:56304
	s_waitcnt lgkmcnt(0)
	s_barrier
; __device__ __forceinline__ void st_tr(bfr* dst, int r0, int c, f32x4 v) { store4b(dst + c * CS + r0, v); }
; __device__ __forceinline__ void ph_r7_ca(const P& p, int j, int win, char* smem) {
;     ...
; #pragma unroll
;     for (int tt = 0; tt < 2; tt++) { const int tj = tj0 + tt, r0 = 16 * ti + 4 * q4, cc = 16 * tj + l15;
;       f32x4 v = cmm(CSLOT(1), CSLOT(0), ti, tj, l15, q4);
; #pragma unroll
;       for (int jj = 0; jj < 4; jj++) if (!(r0 + jj < cc)) v[jj] = 0.f;
;       st_row(CSLOT(7), r0, cc, v); st_tr(CSLOT(8), r0, cc, v);
;       v = cmm(CSLOT(2), CSLOT(0), ti, tj, l15, q4);
; #pragma unroll
;       for (int jj = 0; jj < 4; jj++) if (!(r0 + jj < cc)) v[jj] = 0.f;
;       st_row(CSLOT(9), r0, cc, v);
;       v = cmm(CSLOT(3), CSLOT(1), ti, tj, l15, q4);
; #pragma unroll
;       for (int jj = 0; jj < 4; jj++) if (!(cc <= r0 + jj)) v[jj] = 0.f;
;       st_row(CSLOT(10), r0, cc, v);
;       v = cmm(CSLOT(3), CSLOT(2), ti, tj, l15, q4);
; #pragma unroll
;       for (int jj = 0; jj < 4; jj++) if (!(cc <= r0 + jj)) v[jj] = 0.f;
;       st_row(CSLOT(11), r0, cc, v);
;     }
	ds_read_b128 v[2:5], v63 offset:9216
	ds_read_b128 v[6:9], v63 offset:9280
	ds_read_b128 v[10:13], v63 offset:18432
	ds_read_b128 v[14:17], v63 offset:18496
	ds_read_b128 v[18:21], v63 offset:27648
	ds_read_b128 v[22:25], v63 offset:27712
	ds_read_b128 v[212:215], v109
	ds_read_b128 v[216:219], v109 offset:64
	ds_read_b128 v[220:223], v109 offset:9216
	ds_read_b128 v[224:227], v109 offset:9280
	ds_read_b128 v[228:231], v109 offset:18432
	ds_read_b128 v[232:235], v109 offset:18496
	s_or_b64 vcc, s[56:57], s[54:55]
	s_or_b64 s[88:89], vcc, s[52:53]
	s_or_b64 s[90:91], s[88:89], s[50:51]
	s_waitcnt lgkmcnt(4)
	v_mfma_f32_16x16x32_bf16 v[236:239], v[2:5], v[212:215], 0
	v_mfma_f32_16x16x32_bf16 v[240:243], v[10:13], v[212:215], 0
	v_mfma_f32_16x16x32_bf16 v[236:239], v[6:9], v[216:219], v[236:239]
	v_mfma_f32_16x16x32_bf16 v[240:243], v[14:17], v[216:219], v[240:243]
	s_waitcnt lgkmcnt(2)
	v_mfma_f32_16x16x32_bf16 v[244:247], v[18:21], v[220:223], 0
	v_mfma_f32_16x16x32_bf16 v[244:247], v[22:25], v[224:227], v[244:247]
	s_waitcnt lgkmcnt(0)
	v_mfma_f32_16x16x32_bf16 v[26:29], v[18:21], v[228:231], 0
	v_mfma_f32_16x16x32_bf16 v[26:29], v[22:25], v[232:235], v[26:29]
	ds_read_b128 v[212:215], v124
	ds_read_b128 v[216:219], v124 offset:64
	ds_read_b128 v[220:223], v124 offset:9216
	ds_read_b128 v[224:227], v124 offset:9280
	ds_read_b128 v[228:231], v124 offset:18432
	ds_read_b128 v[232:235], v124 offset:18496
	v_cndmask_b32_e64 v236, 0, v236, s[90:91]
	v_cndmask_b32_e64 v237, 0, v237, s[88:89]
	v_cndmask_b32_e32 v238, 0, v238, vcc
	v_cndmask_b32_e64 v239, 0, v239, s[56:57]
	v_cvt_pk_bf16_f32 v30, v236, s0
	ds_write_b16 v110, v30 offset:64512
	v_cvt_pk_bf16_f32 v31, v237, s0
	ds_write_b16 v110, v31 offset:64656
	v_cvt_pk_bf16_f32 v30, v238, s0
	ds_write_b16 v110, v30 offset:64800
	v_cvt_pk_bf16_f32 v31, v239, s0
	ds_write_b16 v110, v31 offset:64944
	v_cvt_pk_bf16_f32 v236, v236, v237
	v_cvt_pk_bf16_f32 v237, v238, v239
	ds_write_b64 v111, v[236:237]
	v_cndmask_b32_e64 v240, 0, v240, s[90:91]
	v_cndmask_b32_e64 v241, 0, v241, s[88:89]
	v_cndmask_b32_e32 v242, 0, v242, vcc
	v_cndmask_b32_e64 v243, 0, v243, s[56:57]
	v_cvt_pk_bf16_f32 v30, v240, s0
	ds_write_b16 v112, v30
	v_cvt_pk_bf16_f32 v31, v241, s0
	ds_write_b16 v113, v31
	v_cvt_pk_bf16_f32 v30, v242, s0
	ds_write_b16 v114, v30
	v_cvt_pk_bf16_f32 v31, v243, s0
	ds_write_b16 v115, v31
	s_waitcnt lgkmcnt(9)
	v_mfma_f32_16x16x32_bf16 v[236:239], v[18:21], v[220:223], 0
	v_mfma_f32_16x16x32_bf16 v[236:239], v[22:25], v[224:227], v[236:239]
	v_mfma_f32_16x16x32_bf16 v[240:243], v[18:21], v[228:231], 0
	v_mfma_f32_16x16x32_bf16 v[240:243], v[22:25], v[232:235], v[240:243]
	v_cndmask_b32_e64 v244, v244, 0, s[50:51]
	v_cndmask_b32_e64 v245, v245, 0, s[52:53]
	v_cndmask_b32_e64 v246, v246, 0, s[54:55]
	v_cndmask_b32_e64 v247, v247, 0, s[56:57]
	v_cvt_pk_bf16_f32 v30, v244, s0
	ds_write_b16 v116, v30
	v_cvt_pk_bf16_f32 v31, v245, s0
	ds_write_b16 v117, v31
	v_cvt_pk_bf16_f32 v30, v246, s0
	ds_write_b16 v118, v30
	v_cvt_pk_bf16_f32 v31, v247, s0
	ds_write_b16 v119, v31
	v_cndmask_b32_e64 v26, v26, 0, s[50:51]
	v_cndmask_b32_e64 v27, v27, 0, s[52:53]
	v_cndmask_b32_e64 v28, v28, 0, s[54:55]
	v_cndmask_b32_e64 v29, v29, 0, s[56:57]
	v_cvt_pk_bf16_f32 v30, v26, s0
	ds_write_b16 v120, v30
	v_cvt_pk_bf16_f32 v31, v27, s0
	ds_write_b16 v121, v31
	v_cvt_pk_bf16_f32 v30, v28, s0
	ds_write_b16 v122, v30
	v_cvt_pk_bf16_f32 v31, v29, s0
	ds_write_b16 v123, v31
	v_mfma_f32_16x16x32_bf16 v[244:247], v[2:5], v[212:215], 0
	v_mfma_f32_16x16x32_bf16 v[26:29], v[10:13], v[212:215], 0
	v_mfma_f32_16x16x32_bf16 v[244:247], v[6:9], v[216:219], v[244:247]
	v_mfma_f32_16x16x32_bf16 v[26:29], v[14:17], v[216:219], v[26:29]
	s_or_b64 vcc, s[64:65], s[62:63]
	s_or_b64 s[88:89], vcc, s[60:61]
	s_or_b64 s[90:91], s[88:89], s[58:59]
	v_cndmask_b32_e64 v236, v236, 0, s[58:59]
	v_cndmask_b32_e64 v237, v237, 0, s[60:61]
	v_cndmask_b32_e64 v238, v238, 0, s[62:63]
	v_cndmask_b32_e64 v239, v239, 0, s[64:65]
	v_cvt_pk_bf16_f32 v30, v236, s0
	ds_write_b16 v148, v30
	v_cvt_pk_bf16_f32 v31, v237, s0
	ds_write_b16 v149, v31
	v_cvt_pk_bf16_f32 v30, v238, s0
	ds_write_b16 v150, v30
	v_cvt_pk_bf16_f32 v31, v239, s0
	ds_write_b16 v151, v31
	v_cndmask_b32_e64 v240, v240, 0, s[58:59]
	v_cndmask_b32_e64 v241, v241, 0, s[60:61]
	v_cndmask_b32_e64 v242, v242, 0, s[62:63]
	v_cndmask_b32_e64 v243, v243, 0, s[64:65]
	v_cvt_pk_bf16_f32 v30, v240, s0
	ds_write_b16 v152, v30
	v_cvt_pk_bf16_f32 v31, v241, s0
	ds_write_b16 v153, v31
	v_cvt_pk_bf16_f32 v30, v242, s0
	ds_write_b16 v154, v30
	v_cvt_pk_bf16_f32 v31, v243, s0
	ds_write_b16 v155, v31
	v_cndmask_b32_e64 v244, 0, v244, s[90:91]
	v_cndmask_b32_e64 v245, 0, v245, s[88:89]
	v_cndmask_b32_e32 v246, 0, v246, vcc
	v_cndmask_b32_e64 v247, 0, v247, s[64:65]
	v_cvt_pk_bf16_f32 v30, v244, s0
	ds_write_b16 v110, v30 offset:64544
	v_cvt_pk_bf16_f32 v31, v245, s0
	ds_write_b16 v125, v31 offset:64656
	v_cvt_pk_bf16_f32 v30, v246, s0
	ds_write_b16 v125, v30 offset:64800
	v_cvt_pk_bf16_f32 v31, v247, s0
	ds_write_b16 v125, v31 offset:64944
	v_cvt_pk_bf16_f32 v244, v244, v245
	v_cvt_pk_bf16_f32 v245, v246, v247
	ds_write_b64 v126, v[244:245]
	v_cndmask_b32_e64 v26, 0, v26, s[90:91]
	v_cndmask_b32_e64 v27, 0, v27, s[88:89]
	v_cndmask_b32_e32 v28, 0, v28, vcc
	v_cndmask_b32_e64 v29, 0, v29, s[64:65]
	v_cvt_pk_bf16_f32 v30, v26, s0
	ds_write_b16 v127, v30
	v_cvt_pk_bf16_f32 v31, v27, s0
	ds_write_b16 v128, v31
	v_cvt_pk_bf16_f32 v30, v28, s0
	ds_write_b16 v129, v30
	v_cvt_pk_bf16_f32 v31, v29, s0
	ds_write_b16 v147, v31
	s_waitcnt lgkmcnt(0)
	s_barrier
; __device__ __forceinline__ float b2f(bfr b) { return __uint_as_float(((unsigned)b) << 16); }
; __device__ __forceinline__ void ph_r7_ca(const P& p, int j, int win, char* smem) {
;     ...
;       const int cl = lane >> 3, pp = lane & 7, cx = 8 * w + cl, blk0 = (w >> 1) * 16;
; #pragma unroll 1
;       for (int il = 15; il >= 0; il--) { const int i = blk0 + il;
;         float sum = 0.f;
; #pragma unroll 1
;         for (int jx = i + 1 + pp; jx < blk0 + 16; jx += 8) sum += b2f(Ab[i * CS + jx]) * X[jx * 72 + cx];
;         sum += dppf<0xB1>(sum); sum += dppf<0x4E>(sum); sum += dppf<0x141>(sum);
;         const float xv = (i == cx ? 1.f : 0.f) - sum;
;         if (pp == 0) X[i * 72 + cx] = xv;
	v_and_b32_e32 v8, 7, v35
	v_bfe_u32 v9, v35, 3, 4
	v_add_u32_e32 v10, v53, v8
	v_mul_u32_u24_e32 v11, 0x120, v10
	v_add_u32_e32 v11, v11, v34
	v_lshlrev_b32_e32 v10, 1, v10
	s_movk_i32 s28, 0x90
	v_mad_u32_u24 v10, v53, s28, v10
	v_add_u32_e32 v10, 0xfc00, v10
	ds_read_u16 v227, v10 offset:2160
	ds_read_u16 v243, v10 offset:2176
	ds_read_u16 v226, v10 offset:2016
	ds_read_u16 v242, v10 offset:2032
	ds_read_u16 v225, v10 offset:1872
	ds_read_u16 v241, v10 offset:1888
	ds_read_u16 v224, v10 offset:1728
	ds_read_u16 v240, v10 offset:1744
	ds_read_u16 v223, v10 offset:1584
	ds_read_u16 v239, v10 offset:1600
	ds_read_u16 v222, v10 offset:1440
	ds_read_u16 v238, v10 offset:1456
	ds_read_u16 v221, v10 offset:1296
	ds_read_u16 v237, v10 offset:1312
	ds_read_u16 v220, v10 offset:1152
	ds_read_u16 v236, v10 offset:1168
	ds_read_u16 v219, v10 offset:1008
	ds_read_u16 v235, v10 offset:1024
	ds_read_u16 v218, v10 offset:864
	ds_read_u16 v234, v10 offset:880
	ds_read_u16 v217, v10 offset:720
	ds_read_u16 v233, v10 offset:736
	ds_read_u16 v216, v10 offset:576
	ds_read_u16 v232, v10 offset:592
	ds_read_u16 v215, v10 offset:432
	ds_read_u16 v231, v10 offset:448
	ds_read_u16 v214, v10 offset:288
	ds_read_u16 v230, v10 offset:304
	ds_read_u16 v213, v10 offset:144
	ds_read_u16 v229, v10 offset:160
	ds_read_u16 v212, v10 offset:0
	ds_read_u16 v228, v10 offset:16
	v_mov_b32_e32 v2, 0
	v_mov_b32_e32 v3, 0
	s_waitcnt lgkmcnt(0)
	v_lshlrev_b32_e32 v227, 16, v227
	v_lshlrev_b32_e32 v243, 16, v243
	v_cmp_eq_u32_e64 s[88:89], 15, v9
	v_cmp_eq_u32_e32 vcc, 7, v8
	v_mul_f32_e32 v4, v227, v2
	v_fmac_f32_e32 v4, v243, v3
	v_cndmask_b32_e64 v7, 0, 1.0, s[88:89]
	v_lshlrev_b32_e32 v226, 16, v226
	v_add_f32_dpp v4, v4, v4 quad_perm:[1,0,3,2] row_mask:0xf bank_mask:0xf bound_ctrl:1
	v_lshlrev_b32_e32 v242, 16, v242
	s_nop 0
	v_add_f32_dpp v4, v4, v4 quad_perm:[2,3,0,1] row_mask:0xf bank_mask:0xf bound_ctrl:1
	s_nop 1
	v_mov_b32_dpp v5, v4 row_half_mirror row_mask:0xf bank_mask:0xf bound_ctrl:1
	v_add_f32_e32 v4, v4, v5
	v_sub_f32_e32 v6, v7, v4
	v_cndmask_b32_e32 v3, v3, v6, vcc
	v_cmp_eq_u32_e64 s[88:89], 14, v9
	v_cmp_eq_u32_e32 vcc, 6, v8
	v_mul_f32_e32 v4, v226, v2
	v_fmac_f32_e32 v4, v242, v3
	v_cndmask_b32_e64 v7, 0, 1.0, s[88:89]
	v_lshlrev_b32_e32 v225, 16, v225
	v_add_f32_dpp v4, v4, v4 quad_perm:[1,0,3,2] row_mask:0xf bank_mask:0xf bound_ctrl:1
	v_lshlrev_b32_e32 v241, 16, v241
	s_nop 0
	v_add_f32_dpp v4, v4, v4 quad_perm:[2,3,0,1] row_mask:0xf bank_mask:0xf bound_ctrl:1
	s_nop 1
	v_mov_b32_dpp v5, v4 row_half_mirror row_mask:0xf bank_mask:0xf bound_ctrl:1
	v_add_f32_e32 v4, v4, v5
	v_sub_f32_e32 v6, v7, v4
	v_cndmask_b32_e32 v3, v3, v6, vcc
	v_cmp_eq_u32_e64 s[88:89], 13, v9
	v_cmp_eq_u32_e32 vcc, 5, v8
	v_mul_f32_e32 v4, v225, v2
	v_fmac_f32_e32 v4, v241, v3
	v_cndmask_b32_e64 v7, 0, 1.0, s[88:89]
	v_lshlrev_b32_e32 v224, 16, v224
	v_add_f32_dpp v4, v4, v4 quad_perm:[1,0,3,2] row_mask:0xf bank_mask:0xf bound_ctrl:1
	v_lshlrev_b32_e32 v240, 16, v240
	s_nop 0
	v_add_f32_dpp v4, v4, v4 quad_perm:[2,3,0,1] row_mask:0xf bank_mask:0xf bound_ctrl:1
	s_nop 1
	v_mov_b32_dpp v5, v4 row_half_mirror row_mask:0xf bank_mask:0xf bound_ctrl:1
	v_add_f32_e32 v4, v4, v5
	v_sub_f32_e32 v6, v7, v4
	v_cndmask_b32_e32 v3, v3, v6, vcc
	v_cmp_eq_u32_e64 s[88:89], 12, v9
	v_cmp_eq_u32_e32 vcc, 4, v8
	v_mul_f32_e32 v4, v224, v2
	v_fmac_f32_e32 v4, v240, v3
	v_cndmask_b32_e64 v7, 0, 1.0, s[88:89]
	v_lshlrev_b32_e32 v223, 16, v223
	v_add_f32_dpp v4, v4, v4 quad_perm:[1,0,3,2] row_mask:0xf bank_mask:0xf bound_ctrl:1
	v_lshlrev_b32_e32 v239, 16, v239
	s_nop 0
	v_add_f32_dpp v4, v4, v4 quad_perm:[2,3,0,1] row_mask:0xf bank_mask:0xf bound_ctrl:1
	s_nop 1
	v_mov_b32_dpp v5, v4 row_half_mirror row_mask:0xf bank_mask:0xf bound_ctrl:1
	v_add_f32_e32 v4, v4, v5
	v_sub_f32_e32 v6, v7, v4
	v_cndmask_b32_e32 v3, v3, v6, vcc
	v_cmp_eq_u32_e64 s[88:89], 11, v9
	v_cmp_eq_u32_e32 vcc, 3, v8
	v_mul_f32_e32 v4, v223, v2
	v_fmac_f32_e32 v4, v239, v3
	v_cndmask_b32_e64 v7, 0, 1.0, s[88:89]
	v_lshlrev_b32_e32 v222, 16, v222
	v_add_f32_dpp v4, v4, v4 quad_perm:[1,0,3,2] row_mask:0xf bank_mask:0xf bound_ctrl:1
	v_lshlrev_b32_e32 v238, 16, v238
	s_nop 0
	v_add_f32_dpp v4, v4, v4 quad_perm:[2,3,0,1] row_mask:0xf bank_mask:0xf bound_ctrl:1
	s_nop 1
	v_mov_b32_dpp v5, v4 row_half_mirror row_mask:0xf bank_mask:0xf bound_ctrl:1
	v_add_f32_e32 v4, v4, v5
	v_sub_f32_e32 v6, v7, v4
	v_cndmask_b32_e32 v3, v3, v6, vcc
	v_cmp_eq_u32_e64 s[88:89], 10, v9
	v_cmp_eq_u32_e32 vcc, 2, v8
	v_mul_f32_e32 v4, v222, v2
	v_fmac_f32_e32 v4, v238, v3
	v_cndmask_b32_e64 v7, 0, 1.0, s[88:89]
	v_lshlrev_b32_e32 v221, 16, v221
	v_add_f32_dpp v4, v4, v4 quad_perm:[1,0,3,2] row_mask:0xf bank_mask:0xf bound_ctrl:1
	v_lshlrev_b32_e32 v237, 16, v237
	s_nop 0
	v_add_f32_dpp v4, v4, v4 quad_perm:[2,3,0,1] row_mask:0xf bank_mask:0xf bound_ctrl:1
	s_nop 1
	v_mov_b32_dpp v5, v4 row_half_mirror row_mask:0xf bank_mask:0xf bound_ctrl:1
	v_add_f32_e32 v4, v4, v5
	v_sub_f32_e32 v6, v7, v4
	v_cndmask_b32_e32 v3, v3, v6, vcc
	v_cmp_eq_u32_e64 s[88:89], 9, v9
	v_cmp_eq_u32_e32 vcc, 1, v8
	v_mul_f32_e32 v4, v221, v2
	v_fmac_f32_e32 v4, v237, v3
	v_cndmask_b32_e64 v7, 0, 1.0, s[88:89]
	v_lshlrev_b32_e32 v220, 16, v220
	v_add_f32_dpp v4, v4, v4 quad_perm:[1,0,3,2] row_mask:0xf bank_mask:0xf bound_ctrl:1
	v_lshlrev_b32_e32 v236, 16, v236
	s_nop 0
	v_add_f32_dpp v4, v4, v4 quad_perm:[2,3,0,1] row_mask:0xf bank_mask:0xf bound_ctrl:1
	s_nop 1
	v_mov_b32_dpp v5, v4 row_half_mirror row_mask:0xf bank_mask:0xf bound_ctrl:1
	v_add_f32_e32 v4, v4, v5
	v_sub_f32_e32 v6, v7, v4
	v_cndmask_b32_e32 v3, v3, v6, vcc
	v_cmp_eq_u32_e64 s[88:89], 8, v9
	v_cmp_eq_u32_e32 vcc, 0, v8
; __device__ __forceinline__ float b2f(bfr b) { return __uint_as_float(((unsigned)b) << 16); }
; __device__ __forceinline__ void ph_r7_ca(const P& p, int j, int win, char* smem) {
;     ...
;       const int cl = lane >> 3, pp = lane & 7, cx = 8 * w + cl, blk0 = (w >> 1) * 16;
; #pragma unroll 1
;       for (int il = 15; il >= 0; il--) { const int i = blk0 + il;
;         float sum = 0.f;
; #pragma unroll 1
;         for (int jx = i + 1 + pp; jx < blk0 + 16; jx += 8) sum += b2f(Ab[i * CS + jx]) * X[jx * 72 + cx];
;         sum += dppf<0xB1>(sum); sum += dppf<0x4E>(sum); sum += dppf<0x141>(sum);
;         const float xv = (i == cx ? 1.f : 0.f) - sum;
;         if (pp == 0) X[i * 72 + cx] = xv;
;       }
;       __syncthreads();
	v_mul_f32_e32 v4, v220, v2
	v_fmac_f32_e32 v4, v236, v3
	v_cndmask_b32_e64 v7, 0, 1.0, s[88:89]
	v_lshlrev_b32_e32 v219, 16, v219
	v_add_f32_dpp v4, v4, v4 quad_perm:[1,0,3,2] row_mask:0xf bank_mask:0xf bound_ctrl:1
	v_lshlrev_b32_e32 v235, 16, v235
	s_nop 0
	v_add_f32_dpp v4, v4, v4 quad_perm:[2,3,0,1] row_mask:0xf bank_mask:0xf bound_ctrl:1
	s_nop 1
	v_mov_b32_dpp v5, v4 row_half_mirror row_mask:0xf bank_mask:0xf bound_ctrl:1
	v_add_f32_e32 v4, v4, v5
	v_sub_f32_e32 v6, v7, v4
	v_cndmask_b32_e32 v3, v3, v6, vcc
	v_cmp_eq_u32_e64 s[88:89], 7, v9
	v_cmp_eq_u32_e32 vcc, 7, v8
	v_mul_f32_e32 v4, v219, v2
	v_fmac_f32_e32 v4, v235, v3
	v_cndmask_b32_e64 v7, 0, 1.0, s[88:89]
	v_lshlrev_b32_e32 v218, 16, v218
	v_add_f32_dpp v4, v4, v4 quad_perm:[1,0,3,2] row_mask:0xf bank_mask:0xf bound_ctrl:1
	v_lshlrev_b32_e32 v234, 16, v234
	s_nop 0
	v_add_f32_dpp v4, v4, v4 quad_perm:[2,3,0,1] row_mask:0xf bank_mask:0xf bound_ctrl:1
	s_nop 1
	v_mov_b32_dpp v5, v4 row_half_mirror row_mask:0xf bank_mask:0xf bound_ctrl:1
	v_add_f32_e32 v4, v4, v5
	v_sub_f32_e32 v6, v7, v4
	v_cndmask_b32_e32 v2, v2, v6, vcc
	v_cmp_eq_u32_e64 s[88:89], 6, v9
	v_cmp_eq_u32_e32 vcc, 6, v8
	v_mul_f32_e32 v4, v218, v2
	v_fmac_f32_e32 v4, v234, v3
	v_cndmask_b32_e64 v7, 0, 1.0, s[88:89]
	v_lshlrev_b32_e32 v217, 16, v217
	v_add_f32_dpp v4, v4, v4 quad_perm:[1,0,3,2] row_mask:0xf bank_mask:0xf bound_ctrl:1
	v_lshlrev_b32_e32 v233, 16, v233
	s_nop 0
	v_add_f32_dpp v4, v4, v4 quad_perm:[2,3,0,1] row_mask:0xf bank_mask:0xf bound_ctrl:1
	s_nop 1
	v_mov_b32_dpp v5, v4 row_half_mirror row_mask:0xf bank_mask:0xf bound_ctrl:1
	v_add_f32_e32 v4, v4, v5
	v_sub_f32_e32 v6, v7, v4
	v_cndmask_b32_e32 v2, v2, v6, vcc
	v_cmp_eq_u32_e64 s[88:89], 5, v9
	v_cmp_eq_u32_e32 vcc, 5, v8
	v_mul_f32_e32 v4, v217, v2
	v_fmac_f32_e32 v4, v233, v3
	v_cndmask_b32_e64 v7, 0, 1.0, s[88:89]
	v_lshlrev_b32_e32 v216, 16, v216
	v_add_f32_dpp v4, v4, v4 quad_perm:[1,0,3,2] row_mask:0xf bank_mask:0xf bound_ctrl:1
	v_lshlrev_b32_e32 v232, 16, v232
	s_nop 0
	v_add_f32_dpp v4, v4, v4 quad_perm:[2,3,0,1] row_mask:0xf bank_mask:0xf bound_ctrl:1
	s_nop 1
	v_mov_b32_dpp v5, v4 row_half_mirror row_mask:0xf bank_mask:0xf bound_ctrl:1
	v_add_f32_e32 v4, v4, v5
	v_sub_f32_e32 v6, v7, v4
	v_cndmask_b32_e32 v2, v2, v6, vcc
	v_cmp_eq_u32_e64 s[88:89], 4, v9
	v_cmp_eq_u32_e32 vcc, 4, v8
	v_mul_f32_e32 v4, v216, v2
	v_fmac_f32_e32 v4, v232, v3
	v_cndmask_b32_e64 v7, 0, 1.0, s[88:89]
	v_lshlrev_b32_e32 v215, 16, v215
	v_add_f32_dpp v4, v4, v4 quad_perm:[1,0,3,2] row_mask:0xf bank_mask:0xf bound_ctrl:1
	v_lshlrev_b32_e32 v231, 16, v231
	s_nop 0
	v_add_f32_dpp v4, v4, v4 quad_perm:[2,3,0,1] row_mask:0xf bank_mask:0xf bound_ctrl:1
	s_nop 1
	v_mov_b32_dpp v5, v4 row_half_mirror row_mask:0xf bank_mask:0xf bound_ctrl:1
	v_add_f32_e32 v4, v4, v5
	v_sub_f32_e32 v6, v7, v4
	v_cndmask_b32_e32 v2, v2, v6, vcc
	v_cmp_eq_u32_e64 s[88:89], 3, v9
	v_cmp_eq_u32_e32 vcc, 3, v8
	v_mul_f32_e32 v4, v215, v2
	v_fmac_f32_e32 v4, v231, v3
	v_cndmask_b32_e64 v7, 0, 1.0, s[88:89]
	v_lshlrev_b32_e32 v214, 16, v214
	v_add_f32_dpp v4, v4, v4 quad_perm:[1,0,3,2] row_mask:0xf bank_mask:0xf bound_ctrl:1
	v_lshlrev_b32_e32 v230, 16, v230
	s_nop 0
	v_add_f32_dpp v4, v4, v4 quad_perm:[2,3,0,1] row_mask:0xf bank_mask:0xf bound_ctrl:1
	s_nop 1
	v_mov_b32_dpp v5, v4 row_half_mirror row_mask:0xf bank_mask:0xf bound_ctrl:1
	v_add_f32_e32 v4, v4, v5
	v_sub_f32_e32 v6, v7, v4
	v_cndmask_b32_e32 v2, v2, v6, vcc
	v_cmp_eq_u32_e64 s[88:89], 2, v9
	v_cmp_eq_u32_e32 vcc, 2, v8
	v_mul_f32_e32 v4, v214, v2
	v_fmac_f32_e32 v4, v230, v3
	v_cndmask_b32_e64 v7, 0, 1.0, s[88:89]
	v_lshlrev_b32_e32 v213, 16, v213
	v_add_f32_dpp v4, v4, v4 quad_perm:[1,0,3,2] row_mask:0xf bank_mask:0xf bound_ctrl:1
	v_lshlrev_b32_e32 v229, 16, v229
	s_nop 0
	v_add_f32_dpp v4, v4, v4 quad_perm:[2,3,0,1] row_mask:0xf bank_mask:0xf bound_ctrl:1
	s_nop 1
	v_mov_b32_dpp v5, v4 row_half_mirror row_mask:0xf bank_mask:0xf bound_ctrl:1
	v_add_f32_e32 v4, v4, v5
	v_sub_f32_e32 v6, v7, v4
	v_cndmask_b32_e32 v2, v2, v6, vcc
	v_cmp_eq_u32_e64 s[88:89], 1, v9
	v_cmp_eq_u32_e32 vcc, 1, v8
	v_mul_f32_e32 v4, v213, v2
	v_fmac_f32_e32 v4, v229, v3
	v_cndmask_b32_e64 v7, 0, 1.0, s[88:89]
	v_lshlrev_b32_e32 v212, 16, v212
	v_add_f32_dpp v4, v4, v4 quad_perm:[1,0,3,2] row_mask:0xf bank_mask:0xf bound_ctrl:1
	v_lshlrev_b32_e32 v228, 16, v228
	s_nop 0
	v_add_f32_dpp v4, v4, v4 quad_perm:[2,3,0,1] row_mask:0xf bank_mask:0xf bound_ctrl:1
	s_nop 1
	v_mov_b32_dpp v5, v4 row_half_mirror row_mask:0xf bank_mask:0xf bound_ctrl:1
	v_add_f32_e32 v4, v4, v5
	v_sub_f32_e32 v6, v7, v4
	v_cndmask_b32_e32 v2, v2, v6, vcc
	v_cmp_eq_u32_e64 s[88:89], 0, v9
	v_cmp_eq_u32_e32 vcc, 0, v8
	v_mul_f32_e32 v4, v212, v2
	v_fmac_f32_e32 v4, v228, v3
	v_cndmask_b32_e64 v7, 0, 1.0, s[88:89]
	s_nop 0
	v_add_f32_dpp v4, v4, v4 quad_perm:[1,0,3,2] row_mask:0xf bank_mask:0xf bound_ctrl:1
	s_nop 0
	s_nop 0
	v_add_f32_dpp v4, v4, v4 quad_perm:[2,3,0,1] row_mask:0xf bank_mask:0xf bound_ctrl:1
	s_nop 1
	v_mov_b32_dpp v5, v4 row_half_mirror row_mask:0xf bank_mask:0xf bound_ctrl:1
	v_add_f32_e32 v4, v4, v5
	v_sub_f32_e32 v6, v7, v4
	v_cndmask_b32_e32 v2, v2, v6, vcc
	ds_write_b32 v11, v2
	ds_write_b32 v11, v3 offset:2304
; __device__ __forceinline__ bfr f2b(float f) { return (bfr)(cvtpk(f, f) & 0xffffu); }
; __device__ __forceinline__ void st_tr(bfr* dst, int r0, int c, f32x4 v) { store4b(dst + c * CS + r0, v); }
; __device__ __forceinline__ void ph_r7_ca(const P& p, int j, int win, char* smem) {
;     ...
;       __syncthreads();
; #pragma unroll 4
;       for (int e = tid; e < 4096; e += 512) { const int i = e >> 6, c2 = e & 63; const bfr tv = ((i >> 4) == (c2 >> 4)) ? f2b(X[i * 72 + c2]) : (bfr)0; CSLOT(2)[i * CS + c2] = tv; CSLOT(12)[c2 * CS + i] = tv; }
;       __syncthreads();
; #pragma unroll
;       for (int tt = 0; tt < 2; tt++) { const int tj = tj0 + tt, r0 = 16 * ti + 4 * q4, cc = 16 * tj + l15; st_row(CSLOT(13), r0, cc, cmm_mask<1>(CSLOT(2), CSLOT(8), ti, tj, l15, q4)); }
;       __syncthreads();
; #pragma unroll
;       for (int tt = 0; tt < 2; tt++) { const int tj = tj0 + tt, r0 = 16 * ti + 4 * q4, cc = 16 * tj + l15;
;         f32x4 v = ld_row(CSLOT(2), r0, cc) - cmm(CSLOT(13), CSLOT(12), ti, tj, l15, q4); st_row(CSLOT(0), r0, cc, v); st_tr(CSLOT(1), r0, cc, v); }
;       __syncthreads();
.LBB0_232:
	s_waitcnt lgkmcnt(0)
	s_barrier
	v_lshrrev_b32_e32 v2, 6, v35
	v_cmp_eq_u32_e64 s[86:87], 0, v39
	v_cmp_eq_u32_e64 s[88:89], 1, v39
	v_cmp_eq_u32_e64 s[90:91], 2, v39
	v_cmp_eq_u32_e64 s[40:41], 3, v39
	v_mul_u32_u24_e32 v3, 0x120, v2
	v_add_u32_e32 v3, v3, v36
	v_mul_u32_u24_e32 v4, 0x90, v2
	v_add_u32_e32 v4, v4, v38
	v_lshl_add_u32 v5, v2, 1, v156
	v_mov_b32_e32 v6, 0
	v_mov_b32_e32 v7, 0
	v_mov_b32_e32 v8, 0
	v_mov_b32_e32 v9, 0
	v_mov_b32_e32 v10, 0
	v_mov_b32_e32 v11, 0
	v_mov_b32_e32 v12, 0
	v_mov_b32_e32 v13, 0
	s_and_saveexec_b64 s[30:31], s[86:87]
	ds_read_b32 v6, v3 offset:0
	ds_read_b32 v7, v3 offset:2304
	s_or_b64 exec, exec, s[30:31]
	s_and_saveexec_b64 s[30:31], s[88:89]
	ds_read_b32 v8, v3 offset:4608
	ds_read_b32 v9, v3 offset:6912
	s_or_b64 exec, exec, s[30:31]
	s_and_saveexec_b64 s[30:31], s[90:91]
	ds_read_b32 v10, v3 offset:9216
	ds_read_b32 v11, v3 offset:11520
	s_or_b64 exec, exec, s[30:31]
	s_and_saveexec_b64 s[30:31], s[40:41]
	ds_read_b32 v12, v3 offset:13824
	ds_read_b32 v13, v3 offset:16128
	s_or_b64 exec, exec, s[30:31]
	s_waitcnt lgkmcnt(0)
	v_cvt_pk_bf16_f32 v6, v6, s0
	v_cvt_pk_bf16_f32 v7, v7, s0
	v_cvt_pk_bf16_f32 v8, v8, s0
	v_cvt_pk_bf16_f32 v9, v9, s0
	v_cvt_pk_bf16_f32 v10, v10, s0
	v_cvt_pk_bf16_f32 v11, v11, s0
	v_cvt_pk_bf16_f32 v12, v12, s0
	v_cvt_pk_bf16_f32 v13, v13, s0
	ds_write_b16 v4, v6 offset:18432
	ds_write_b16 v5, v6 offset:0
	ds_write_b16 v4, v7 offset:19584
	ds_write_b16 v5, v7 offset:16
	ds_write_b16 v4, v8 offset:20736
	ds_write_b16 v5, v8 offset:32
	ds_write_b16 v4, v9 offset:21888
	ds_write_b16 v5, v9 offset:48
	ds_write_b16 v4, v10 offset:23040
	ds_write_b16 v5, v10 offset:64
	ds_write_b16 v4, v11 offset:24192
	ds_write_b16 v5, v11 offset:80
	ds_write_b16 v4, v12 offset:25344
	ds_write_b16 v5, v12 offset:96
	ds_write_b16 v4, v13 offset:26496
	ds_write_b16 v5, v13 offset:112
	s_waitcnt lgkmcnt(0)
	s_barrier
	ds_read_b128 v[4:7], v63 offset:18432
	ds_read_b128 v[10:13], v63 offset:18496
	v_readlane_b32 s8, v255, 1
	v_readlane_b32 s9, v255, 2
	v_mov_b32_e32 v20, 0
	v_mov_b32_e32 v21, 0
	v_mov_b32_e32 v22, 0
	v_mov_b32_e32 v23, 0
	v_mov_b32_e32 v24, 0
	v_mov_b32_e32 v25, 0
	v_mov_b32_e32 v26, 0
	v_mov_b32_e32 v27, 0
	v_mov_b32_e32 v0, 0
	s_and_saveexec_b64 s[30:31], s[8:9]
	ds_read_b128 v[20:23], v211
	s_or_b64 exec, exec, s[30:31]
	s_and_saveexec_b64 s[30:31], s[6:7]
	ds_read_b128 v[24:27], v211 offset:64
	s_or_b64 exec, exec, s[30:31]
	ds_write_b16 v158, v0
	ds_write_b16 v158, v0 offset:144
	ds_write_b16 v158, v0 offset:288
	ds_write_b16 v158, v0 offset:432
	s_waitcnt lgkmcnt(4)
	v_mfma_f32_16x16x32_bf16 v[14:17], v[4:7], v[20:23], 0
	v_mfma_f32_16x16x32_bf16 v[14:17], v[10:13], v[24:27], v[14:17]
	s_nop 7
	s_nop 1
	v_cvt_pk_bf16_f32 v30, v14, s0
	ds_write_b16 v159, v30
	v_cvt_pk_bf16_f32 v31, v15, s0
	ds_write_b16 v159, v31 offset:144
	v_cvt_pk_bf16_f32 v30, v16, s0
	ds_write_b16 v159, v30 offset:288
	v_cvt_pk_bf16_f32 v31, v17, s0
	ds_write_b16 v159, v31 offset:432
	s_waitcnt lgkmcnt(0)
	s_barrier
	ds_read_u16 v2, v110 offset:18432
	ds_read_u16 v3, v110 offset:18576
	ds_read_u16 v4, v110 offset:18720
	ds_read_u16 v5, v110 offset:18864
	ds_read_u16 v6, v110 offset:18464
	ds_read_u16 v7, v125 offset:18576
	ds_read_u16 v8, v125 offset:18720
	ds_read_u16 v9, v125 offset:18864
	ds_read_b128 v[10:13], v68
	ds_read_b128 v[14:17], v68 offset:64
	ds_read_b128 v[212:215], v160
	ds_read_b128 v[216:219], v160 offset:64
	ds_read_b128 v[220:223], v162
	ds_read_b128 v[224:227], v162 offset:64
	s_waitcnt lgkmcnt(2)
	v_mfma_f32_16x16x32_bf16 v[228:231], v[10:13], v[212:215], 0
	v_mfma_f32_16x16x32_bf16 v[228:231], v[14:17], v[216:219], v[228:231]
	s_waitcnt lgkmcnt(0)
	v_mfma_f32_16x16x32_bf16 v[232:235], v[10:13], v[220:223], 0
	v_mfma_f32_16x16x32_bf16 v[232:235], v[14:17], v[224:227], v[232:235]
	v_lshlrev_b32_e32 v2, 16, v2
	v_lshlrev_b32_e32 v3, 16, v3
	v_lshlrev_b32_e32 v4, 16, v4
	v_lshlrev_b32_e32 v5, 16, v5
	v_lshlrev_b32_e32 v6, 16, v6
	v_lshlrev_b32_e32 v7, 16, v7
	v_lshlrev_b32_e32 v8, 16, v8
	v_lshlrev_b32_e32 v9, 16, v9
	s_nop 1
	v_sub_f32_e32 v228, v2, v228
	v_sub_f32_e32 v229, v3, v229
	v_sub_f32_e32 v230, v4, v230
	v_sub_f32_e32 v231, v5, v231
	v_cvt_pk_bf16_f32 v30, v228, s0
	ds_write_b16 v110, v30
	v_cvt_pk_bf16_f32 v31, v229, s0
	ds_write_b16 v110, v31 offset:144
	v_cvt_pk_bf16_f32 v30, v230, s0
	ds_write_b16 v110, v30 offset:288
	v_cvt_pk_bf16_f32 v31, v231, s0
	ds_write_b16 v110, v31 offset:432
	v_cvt_pk_bf16_f32 v228, v228, v229
	v_cvt_pk_bf16_f32 v229, v230, v231
	ds_write_b64 v161, v[228:229] offset:9216
	v_sub_f32_e32 v232, v6, v232
	v_sub_f32_e32 v233, v7, v233
	v_sub_f32_e32 v234, v8, v234
	v_sub_f32_e32 v235, v9, v235
	v_cvt_pk_bf16_f32 v30, v232, s0
	ds_write_b16 v110, v30 offset:32
	v_cvt_pk_bf16_f32 v31, v233, s0
	ds_write_b16 v125, v31 offset:144
	v_cvt_pk_bf16_f32 v30, v234, s0
	ds_write_b16 v125, v30 offset:288
	v_cvt_pk_bf16_f32 v31, v235, s0
	ds_write_b16 v125, v31 offset:432
	v_cvt_pk_bf16_f32 v232, v232, v233
	v_cvt_pk_bf16_f32 v233, v234, v235
	ds_write_b64 v163, v[232:233] offset:9216
	v_mov_b32_e32 v10, 0
	v_mov_b32_e32 v11, 0
	v_mov_b32_e32 v12, 0
	s_waitcnt lgkmcnt(0)
	s_barrier
; __device__ __forceinline__ void ph_r7_ca(const P& p, int j, int win, char* smem) {
;     ...
;       for (int tt = 0; tt < 2; tt++) { const int tj = tj0 + tt, r0 = 16 * ti + 4 * q4, cc = 16 * tj + l15; st_row(CSLOT(13), r0, cc, cmm_mask<2>(CSLOT(0), CSLOT(8), ti, tj, l15, q4)); }
;       __syncthreads();
; #pragma unroll
;       for (int tt = 0; tt < 2; tt++) { const int tj = tj0 + tt, r0 = 16 * ti + 4 * q4, cc = 16 * tj + l15;
;         f32x4 v = ld_row(CSLOT(0), r0, cc) - cmm(CSLOT(13), CSLOT(1), ti, tj, l15, q4);
; #pragma unroll
;         for (int jj = 0; jj < 4; jj++) if (r0 + jj == cc) v[jj] -= 1.f;
;         st_row(CSLOT(2), r0, cc, v); }
	ds_read_b128 v[6:9], v63
	v_mov_b32_e32 v10, 0
	v_mov_b32_e32 v11, 0
	v_mov_b32_e32 v12, 0
	v_mov_b32_e32 v13, 0
	v_mov_b32_e32 v20, 0
	v_mov_b32_e32 v21, 0
	v_mov_b32_e32 v22, 0
	v_mov_b32_e32 v23, 0
	v_add_u32_e32 v0, v67, v157
	s_and_saveexec_b64 s[30:31], s[66:67]
	ds_read_b128 v[10:13], v0
	ds_read_b128 v[20:23], v211
	s_or_b64 exec, exec, s[30:31]
	v_add_u32_e32 v18, v62, v157
	s_ashr_i32 s85, s84, 31
	s_lshl_b64 s[30:31], s[84:85], 15
	s_add_u32 s30, s24, s30
	s_addc_u32 s31, s25, s31
	v_lshl_add_u64 v[48:49], v[32:33], 1, s[30:31]
	v_mov_b32_e32 v43, v1
	s_mov_b64 s[30:31], 0x2000
	v_lshl_add_u64 v[46:47], v[48:49], 0, s[30:31]
	s_waitcnt lgkmcnt(0)
	v_mfma_f32_16x16x32_bf16 v[14:17], v[6:9], v[10:13], 0
	v_mfma_f32_16x16x32_bf16 v[24:27], v[6:9], v[20:23], 0
	s_nop 7
	s_nop 1
	v_cvt_pk_bf16_f32 v30, v14, s0
	ds_write_b16 v158, v30
	v_cvt_pk_bf16_f32 v31, v15, s0
	ds_write_b16 v158, v31 offset:144
	v_cvt_pk_bf16_f32 v30, v16, s0
	ds_write_b16 v158, v30 offset:288
	v_cvt_pk_bf16_f32 v31, v17, s0
	ds_write_b16 v158, v31 offset:432
	v_cvt_pk_bf16_f32 v30, v24, s0
	ds_write_b16 v159, v30
	v_cvt_pk_bf16_f32 v31, v25, s0
	ds_write_b16 v159, v31 offset:144
	v_cvt_pk_bf16_f32 v30, v26, s0
	ds_write_b16 v159, v30 offset:288
	v_cvt_pk_bf16_f32 v31, v27, s0
	ds_write_b16 v159, v31 offset:432
	s_waitcnt lgkmcnt(0)
	s_barrier
	ds_read_u16 v2, v110
	ds_read_u16 v3, v110 offset:144
	ds_read_u16 v4, v110 offset:288
	ds_read_u16 v5, v110 offset:432
	ds_read_u16 v6, v110 offset:32
	ds_read_u16 v7, v125 offset:144
	ds_read_u16 v8, v125 offset:288
	ds_read_u16 v9, v125 offset:432
	ds_read_b128 v[10:13], v68
	ds_read_b128 v[14:17], v68 offset:64
	ds_read_b128 v[212:215], v18 offset:9216
	ds_read_b128 v[216:219], v18 offset:9280
	ds_read_b128 v[220:223], v210 offset:9216
	ds_read_b128 v[224:227], v210 offset:9280
	s_waitcnt lgkmcnt(2)
	v_mfma_f32_16x16x32_bf16 v[228:231], v[10:13], v[212:215], 0
	v_mfma_f32_16x16x32_bf16 v[228:231], v[14:17], v[216:219], v[228:231]
	s_waitcnt lgkmcnt(0)
	v_mfma_f32_16x16x32_bf16 v[232:235], v[10:13], v[220:223], 0
	v_mfma_f32_16x16x32_bf16 v[232:235], v[14:17], v[224:227], v[232:235]
	v_lshlrev_b32_e32 v2, 16, v2
	v_lshlrev_b32_e32 v3, 16, v3
	v_lshlrev_b32_e32 v4, 16, v4
	v_lshlrev_b32_e32 v5, 16, v5
	v_lshlrev_b32_e32 v6, 16, v6
	v_lshlrev_b32_e32 v7, 16, v7
	v_lshlrev_b32_e32 v8, 16, v8
	v_lshlrev_b32_e32 v9, 16, v9
	s_nop 1
	v_sub_f32_e32 v228, v2, v228
	v_add_f32_e32 v2, -1.0, v228
	v_cndmask_b32_e64 v228, v228, v2, s[68:69]
	v_sub_f32_e32 v229, v3, v229
	v_add_f32_e32 v3, -1.0, v229
	v_cndmask_b32_e64 v229, v229, v3, s[70:71]
	v_sub_f32_e32 v230, v4, v230
	v_add_f32_e32 v4, -1.0, v230
	v_cndmask_b32_e64 v230, v230, v4, s[72:73]
	v_sub_f32_e32 v231, v5, v231
	v_add_f32_e32 v5, -1.0, v231
	v_cndmask_b32_e64 v231, v231, v5, s[74:75]
	v_cvt_pk_bf16_f32 v30, v228, s0
	ds_write_b16 v110, v30 offset:18432
	v_cvt_pk_bf16_f32 v31, v229, s0
	ds_write_b16 v110, v31 offset:18576
	v_cvt_pk_bf16_f32 v30, v230, s0
	ds_write_b16 v110, v30 offset:18720
	v_cvt_pk_bf16_f32 v31, v231, s0
	ds_write_b16 v110, v31 offset:18864
	v_sub_f32_e32 v232, v6, v232
	v_add_f32_e32 v6, -1.0, v232
	v_cndmask_b32_e64 v232, v232, v6, s[76:77]
	v_sub_f32_e32 v233, v7, v233
	v_add_f32_e32 v7, -1.0, v233
	v_cndmask_b32_e64 v233, v233, v7, s[78:79]
	v_sub_f32_e32 v234, v8, v234
	v_add_f32_e32 v8, -1.0, v234
	v_cndmask_b32_e64 v234, v234, v8, s[80:81]
	v_sub_f32_e32 v235, v9, v235
	v_add_f32_e32 v9, -1.0, v235
	v_cndmask_b32_e64 v235, v235, v9, s[82:83]
	v_cvt_pk_bf16_f32 v30, v232, s0
	ds_write_b16 v110, v30 offset:18464
	v_cvt_pk_bf16_f32 v31, v233, s0
	ds_write_b16 v125, v31 offset:18576
	v_cvt_pk_bf16_f32 v30, v234, s0
	ds_write_b16 v125, v30 offset:18720
	v_cvt_pk_bf16_f32 v31, v235, s0
	ds_write_b16 v125, v31 offset:18864
	s_waitcnt lgkmcnt(0)
	s_barrier
; __device__ __forceinline__ void store4b(bfr* dst, f32x4 v) { uint2 u; u.x = pk2(v[0], v[1]); u.y = pk2(v[2], v[3]); *(uint2*)dst = u; }
; __device__ __forceinline__ f32x4 ld_tr(const bfr* src, int r0, int c) { uint2 u = *(const uint2*)(src + c * CS + r0); return f32x4{blo(u.x), bhi(u.x), blo(u.y), bhi(u.y)}; }
; __device__ __forceinline__ void ph_r7_ca(const P& p, int j, int win, char* smem) {
;     ...
;     for (int tt = 0; tt < 2; tt++) { const int tj = tj0 + tt, r0 = 16 * ti + 4 * q4, cc = 16 * tj + l15;
;       f32x4 g = cmm(CSLOT(10), CSLOT(2), ti, tj, l15, q4) + ld_row(CSLOT(10), r0, cc); st_row(CSLOT(12), r0, cc, g);
;       f32x4 hh = cmm(CSLOT(5), CSLOT(2), ti, tj, l15, q4) + ld_row(CSLOT(5), r0, cc); st_row(CSLOT(13), r0, cc, hh); }
;     __syncthreads();
;     {
;       bfr* out = WB + (size_t)(chain * 20 + cl) * 16384;
; #pragma unroll
;       for (int tt = 0; tt < 2; tt++) { const int tj = tj0 + tt, r0 = 16 * ti + 4 * q4, cc = 16 * tj + l15;
;         f32x4 v = ld_tr(CSLOT(3), r0, cc) - cmm(CSLOT(4), CSLOT(12), ti, tj, l15, q4);
;         store4b(out + cc * 64 + r0, v);
;         v = ld_tr(CSLOT(11), r0, cc) - cmm(CSLOT(9), CSLOT(12), ti, tj, l15, q4);
;         store4b(out + 4096 + cc * 64 + r0, v);
;         v = -cmm(CSLOT(4), CSLOT(13), ti, tj, l15, q4);
; #pragma unroll
;         for (int jj = 0; jj < 4; jj++) if (r0 + jj == cc) v[jj] += WL[cc];
;         store4b(out + 8192 + cc * 64 + r0, v);
	ds_read_b128 v[10:13], v69
	ds_read_b128 v[14:17], v69 offset:64
	ds_read_b128 v[212:215], v18 offset:18432
	ds_read_b128 v[216:219], v18 offset:18496
	ds_read_u16 v2, v116
	ds_read_u16 v3, v117
	ds_read_u16 v4, v118
	ds_read_u16 v5, v119
	ds_read_b128 v[20:23], v63 offset:46080
	ds_read_b128 v[24:27], v63 offset:46144
	ds_read_u16 v6, v110 offset:46080
	ds_read_u16 v7, v110 offset:46224
	ds_read_u16 v8, v110 offset:46368
	ds_read_u16 v9, v110 offset:46512
	s_waitcnt lgkmcnt(6)
	v_mfma_f32_16x16x32_bf16 v[228:231], v[10:13], v[212:215], 0
	v_mfma_f32_16x16x32_bf16 v[228:231], v[14:17], v[216:219], v[228:231]
	ds_read_b128 v[220:223], v210 offset:18432
	ds_read_b128 v[224:227], v210 offset:18496
	ds_read_u16 v236, v148
	ds_read_u16 v237, v149
	ds_read_u16 v238, v150
	ds_read_u16 v239, v151
	s_waitcnt lgkmcnt(6)
	v_mfma_f32_16x16x32_bf16 v[232:235], v[20:23], v[212:215], 0
	v_mfma_f32_16x16x32_bf16 v[232:235], v[24:27], v[216:219], v[232:235]
	ds_read_u16 v240, v110 offset:46112
	ds_read_u16 v241, v125 offset:46224
	ds_read_u16 v242, v125 offset:46368
	ds_read_u16 v243, v125 offset:46512
	s_waitcnt lgkmcnt(8)
	v_mfma_f32_16x16x32_bf16 v[244:247], v[10:13], v[220:223], 0
	v_mfma_f32_16x16x32_bf16 v[244:247], v[14:17], v[224:227], v[244:247]
	v_mfma_f32_16x16x32_bf16 v[28:31], v[20:23], v[220:223], 0
	v_mfma_f32_16x16x32_bf16 v[28:31], v[24:27], v[224:227], v[28:31]
	s_waitcnt lgkmcnt(0)
	v_lshlrev_b32_e32 v2, 16, v2
	v_lshlrev_b32_e32 v3, 16, v3
	v_lshlrev_b32_e32 v4, 16, v4
	v_lshlrev_b32_e32 v5, 16, v5
	v_pk_add_f32 v[228:229], v[228:229], v[2:3]
	v_pk_add_f32 v[230:231], v[230:231], v[4:5]
	v_cvt_pk_bf16_f32 v0, v228, s0
	ds_write_b16 v164, v0
	v_cvt_pk_bf16_f32 v2, v229, s0
	ds_write_b16 v165, v2
	v_cvt_pk_bf16_f32 v0, v230, s0
	ds_write_b16 v166, v0
	v_cvt_pk_bf16_f32 v2, v231, s0
	ds_write_b16 v167, v2
	v_lshlrev_b32_e32 v6, 16, v6
	v_lshlrev_b32_e32 v7, 16, v7
	v_lshlrev_b32_e32 v8, 16, v8
	v_lshlrev_b32_e32 v9, 16, v9
	v_pk_add_f32 v[232:233], v[232:233], v[6:7]
	v_pk_add_f32 v[234:235], v[234:235], v[8:9]
	v_cvt_pk_bf16_f32 v0, v232, s0
	ds_write_b16 v187, v0
	v_cvt_pk_bf16_f32 v2, v233, s0
	ds_write_b16 v188, v2
	v_cvt_pk_bf16_f32 v0, v234, s0
	ds_write_b16 v189, v0
	v_cvt_pk_bf16_f32 v2, v235, s0
	ds_write_b16 v190, v2
	v_lshlrev_b32_e32 v236, 16, v236
	v_lshlrev_b32_e32 v237, 16, v237
	v_lshlrev_b32_e32 v238, 16, v238
	v_lshlrev_b32_e32 v239, 16, v239
	v_pk_add_f32 v[244:245], v[244:245], v[236:237]
	v_pk_add_f32 v[246:247], v[246:247], v[238:239]
	v_cvt_pk_bf16_f32 v0, v244, s0
	ds_write_b16 v191, v0
	v_cvt_pk_bf16_f32 v2, v245, s0
	ds_write_b16 v192, v2
	v_cvt_pk_bf16_f32 v0, v246, s0
	ds_write_b16 v193, v0
	v_cvt_pk_bf16_f32 v2, v247, s0
	ds_write_b16 v194, v2
	v_lshlrev_b32_e32 v240, 16, v240
	v_lshlrev_b32_e32 v241, 16, v241
	v_lshlrev_b32_e32 v242, 16, v242
	v_lshlrev_b32_e32 v243, 16, v243
	v_pk_add_f32 v[28:29], v[28:29], v[240:241]
	v_pk_add_f32 v[30:31], v[30:31], v[242:243]
	v_cvt_pk_bf16_f32 v0, v28, s0
	ds_write_b16 v195, v0
	v_cvt_pk_bf16_f32 v2, v29, s0
	ds_write_b16 v196, v2
	v_cvt_pk_bf16_f32 v0, v30, s0
	ds_write_b16 v197, v0
	v_cvt_pk_bf16_f32 v2, v31, s0
	ds_write_b16 v198, v2
	s_waitcnt lgkmcnt(0)
	s_barrier
	ds_read_b64 v[2:3], v161 offset:27648
	ds_read_b128 v[14:17], v63 offset:36864
	ds_read_b128 v[6:9], v160
	ds_read_b128 v[10:13], v63 offset:36928
	ds_read_b128 v[18:21], v160 offset:64
	s_waitcnt lgkmcnt(4)
	v_lshlrev_b32_e32 v0, 16, v2
	v_and_b32_e32 v22, 0xffff0000, v2
	v_lshlrev_b32_e32 v23, 16, v3
	v_and_b32_e32 v24, 0xffff0000, v3
	s_waitcnt lgkmcnt(2)
	v_mfma_f32_16x16x32_bf16 v[2:5], v[14:17], v[6:9], 0
	s_waitcnt lgkmcnt(0)
	v_mfma_f32_16x16x32_bf16 v[2:5], v[10:13], v[18:21], v[2:5]
	s_nop 7
	v_sub_f32_e32 v5, v24, v5
	v_sub_f32_e32 v23, v23, v4
	v_sub_f32_e32 v4, v22, v3
	v_sub_f32_e32 v0, v0, v2
	v_lshl_add_u64 v[2:3], v[48:49], 0, v[42:43]
	v_cvt_pk_bf16_f32 v4, v0, v4
	v_cvt_pk_bf16_f32 v5, v23, v5
	global_store_dwordx2 v[2:3], v[4:5], off
	ds_read_b64 v[2:3], v199
	s_waitcnt lgkmcnt(0)
	v_lshlrev_b32_e32 v0, 16, v2
	v_and_b32_e32 v26, 0xffff0000, v2
	v_lshlrev_b32_e32 v27, 16, v3
	v_and_b32_e32 v28, 0xffff0000, v3
	ds_read_b128 v[2:5], v70
	s_waitcnt lgkmcnt(0)
	v_mfma_f32_16x16x32_bf16 v[22:25], v[2:5], v[6:9], 0
	ds_read_b128 v[6:9], v70 offset:64
	s_waitcnt lgkmcnt(0)
	v_mfma_f32_16x16x32_bf16 v[18:21], v[6:9], v[18:21], v[22:25]
	s_nop 7
	v_sub_f32_e32 v21, v28, v21
	v_sub_f32_e32 v22, v27, v20
	v_sub_f32_e32 v20, v26, v19
	v_sub_f32_e32 v0, v0, v18
	v_lshl_add_u64 v[18:19], v[46:47], 0, v[42:43]
	v_cvt_pk_bf16_f32 v20, v0, v20
	v_cvt_pk_bf16_f32 v21, v22, v21
	global_store_dwordx2 v[18:19], v[20:21], off
	ds_read_b128 v[18:21], v200
	ds_read_b128 v[22:25], v200 offset:64
	s_waitcnt lgkmcnt(1)
	v_mfma_f32_16x16x32_bf16 v[26:29], v[14:17], v[18:21], 0
	s_waitcnt lgkmcnt(0)
	v_mfma_f32_16x16x32_bf16 v[28:31], v[10:13], v[22:25], v[26:29]
	s_nop 7
	v_xor_b32_e32 v27, 0x80000000, v31
	v_xor_b32_e32 v26, 0x80000000, v30
	v_xor_b32_e32 v29, 0x80000000, v29
	v_xor_b32_e32 v0, 0x80000000, v28
	s_and_saveexec_b64 s[30:31], s[68:69]
	s_cbranch_execnz .LBB0_267
	s_or_b64 exec, exec, s[30:31]
	s_and_saveexec_b64 s[30:31], s[70:71]
	s_cbranch_execnz .LBB0_268
